# v062 + PREP: the three per-row-group vmcnt(0) waits that only guarded a 16-bit-to-f32 shift are gone (rope values loaded with global_load_short_d16_hi into zeroed registers), so the three row groups'
# baseline (speedup 1.0000x reference)
.LBB0_353:
	s_ashr_i32 s15, s14, 31
	s_mul_i32 s7, s14, 0x3000
	s_mul_hi_i32 s6, s14, 0x3000
	s_add_u32 s10, s1, s7
	s_addc_u32 s11, s2, s6
	v_lshl_add_u64 v[6:7], v[24:25], 1, s[10:11]
	v_lshl_add_u64 v[8:9], v[6:7], 0, v[34:35]
	global_load_dwordx2 v[42:43], v[6:7], off offset:3072
	global_load_dword v22, v[8:9], off offset:3584
	v_mov_b32_e32 v18, s87
	v_mov_b32_e32 v20, s87
	v_mov_b32_e32 v0, s33
	v_mov_b32_e32 v16, s87
	s_and_saveexec_b64 s[6:7], s[4:5]
	s_cbranch_execz .LBB0_357
	v_lshl_add_u64 v[8:9], v[28:29], 1, s[10:11]
	v_mov_b32_e32 v18, 0
	v_mov_b32_e32 v20, 0
	global_load_short_d16_hi v18, v[8:9], off offset:3840
	global_load_short_d16_hi v20, v[8:9], off offset:3856
	s_cmpk_gt_i32 s14, 0x7fff
	s_cbranch_scc1 .LBB0_356
	s_and_b32 s10, s3, 0xffe0
	v_add_u32_e32 v8, s10, v28
	v_ashrrev_i32_e32 v9, 31, v8
	v_lshl_add_u64 v[8:9], v[8:9], 2, s[8:9]
	global_load_dword v0, v[8:9], off
	global_load_dword v16, v[8:9], off offset:32
.LBB0_356:
.LBB0_357:
	s_or_b64 exec, exec, s[6:7]
	s_add_i32 s10, s14, s0
	v_mov_b32_e32 v11, s87
	v_mov_b32_e32 v13, s87
	v_mov_b32_e32 v7, s33
	v_mov_b32_e32 v9, s87
	s_cmp_gt_i32 s10, 0x8fff
	v_mov_b32_e32 v38, 0
	s_cbranch_scc1 .LBB0_363
	s_mul_i32 s7, s10, 0x3000
	s_mul_hi_i32 s6, s10, 0x3000
	s_add_u32 s12, s1, s7
	s_addc_u32 s13, s2, s6
	v_lshl_add_u64 v[14:15], v[24:25], 1, s[12:13]
	v_lshl_add_u64 v[44:45], v[14:15], 0, v[34:35]
	global_load_dwordx2 v[40:41], v[14:15], off offset:3072
	s_nop 0
	global_load_dword v15, v[44:45], off offset:3584
	s_and_saveexec_b64 s[6:7], s[4:5]
	s_cbranch_execz .LBB0_362
	v_lshl_add_u64 v[44:45], v[28:29], 1, s[12:13]
	v_mov_b32_e32 v11, 0
	v_mov_b32_e32 v13, 0
	global_load_short_d16_hi v11, v[44:45], off offset:3840
	global_load_short_d16_hi v13, v[44:45], off offset:3856
	s_cmpk_gt_i32 s10, 0x7fff
	s_cbranch_scc1 .LBB0_361
	s_add_i32 s11, s21, s3
	s_and_b32 s11, s11, 0xffe0
	v_add_u32_e32 v44, s11, v28
	v_ashrrev_i32_e32 v45, 31, v44
	v_lshl_add_u64 v[44:45], v[44:45], 2, s[8:9]
	global_load_dword v7, v[44:45], off
	global_load_dword v9, v[44:45], off offset:32
.LBB0_361:
.LBB0_362:
	s_or_b64 exec, exec, s[6:7]
	s_branch .LBB0_364

.LBB0_364:
	s_add_i32 s12, s19, s14
	v_mov_b32_e32 v10, s87
	v_mov_b32_e32 v12, s87
	v_mov_b32_e32 v6, s33
	s_cmp_gt_i32 s12, 0x8fff
	v_mov_b32_e32 v8, s87
	s_cbranch_scc1 .LBB0_370
	s_mul_i32 s7, s12, 0x3000
	s_mul_hi_i32 s6, s12, 0x3000
	s_add_u32 s16, s1, s7
	s_addc_u32 s17, s2, s6
	v_lshl_add_u64 v[38:39], v[24:25], 1, s[16:17]
	v_lshl_add_u64 v[44:45], v[38:39], 0, v[34:35]
	global_load_dwordx2 v[38:39], v[38:39], off offset:3072
	s_nop 0
	global_load_dword v14, v[44:45], off offset:3584
	s_and_saveexec_b64 s[6:7], s[4:5]
	s_cbranch_execz .LBB0_369
	v_lshl_add_u64 v[44:45], v[28:29], 1, s[16:17]
	v_mov_b32_e32 v10, 0
	v_mov_b32_e32 v12, 0
	global_load_short_d16_hi v10, v[44:45], off offset:3840
	global_load_short_d16_hi v12, v[44:45], off offset:3856
	s_cmpk_gt_i32 s12, 0x7fff
	s_cbranch_scc1 .LBB0_368
	s_add_i32 s11, s20, s3
	s_and_b32 s11, s11, 0xffe0
	v_add_u32_e32 v44, s11, v28
	v_ashrrev_i32_e32 v45, 31, v44
	v_lshl_add_u64 v[44:45], v[44:45], 2, s[8:9]
	global_load_dword v6, v[44:45], off
	global_load_dword v8, v[44:45], off offset:32
